# combo20: combo19 + EpiQR (rope q epilogue): the two cos/sin/gain load batches of each row group issued together with renamed registers (8 waits per unit instead of 16)
# speedup vs baseline: 1.0101x; 1.0047x over previous
; __device__ __forceinline__ unsigned cvt_pk_bf16(float lo, float hi) { unsigned r; asm volatile("v_cvt_pk_bf16_f32 %0, %1, %2" : "=v"(r) : "v"(lo), "v"(hi)); return r; }
;     __device__ __forceinline__ void operator()(const f32x4 (&acc)[2][2][4][2], const Unit& u, int wr_, int wc_, int fr_, int fq_) const {
;     ...
;                 for (int m = 0; m < 4; ++m) { int rl = ai * HALF + wr * 64 + m * 16 + fr; asm volatile("" : "+v"(rl)); float s = 0.f;
; #pragma unroll
;                     for (int bj = 0; bj < 2; ++bj)
; #pragma unroll
;                         for (int n = 0; n < 2; ++n) { const f32x4 x = acc[ai][bj][m][n]; s += (x[0] * x[0] + x[1] * x[1]) + (x[2] * x[2] + x[3] * x[3]); }
;                     s += __shfl_xor(s, 16); s += __shfl_xor(s, 32);
;                     const float rr = 1.0f / sqrtf(s * (1.0f / 64.0f) + RMS_EPS_F);
;                     const size_t t = (size_t)u.pm * BM + rl;
;                     bf16_t* qrow = Q + ((size_t)(b * 4 + wc) * 8192 + s0 + rl) * 192 + 128;
;                     u32x4 wa, wb;
; #pragma unroll
;                     for (int n = 0; n < 2; ++n) { const int j0 = 8 * fq + 4 * n;
;                         const f32x4 c4 = *(const f32x4*)(cosT + t * 32 + j0), s4 = *(const f32x4*)(sinT + t * 32 + j0);
;                         const f32x4 g1 = *(const f32x4*)(gn_rope + j0), g2 = *(const f32x4*)(gn_rope + 32 + j0);
;                         const f32x4 y1 = acc[ai][0][m][n] * rr * g1, y2 = acc[ai][1][m][n] * rr * g2;
;                         const f32x4 o1 = y1 * c4 - y2 * s4, o2 = y2 * c4 + y1 * s4;
;                         wa[2 * n] = cvt_pk_bf16(o1[0], o1[1]); wa[2 * n + 1] = cvt_pk_bf16(o1[2], o1[3]); wb[2 * n] = cvt_pk_bf16(o2[0], o2[1]); wb[2 * n + 1] = cvt_pk_bf16(o2[2], o2[3]); }
;                     *(u32x4*)(qrow + 8 * fq) = wa; *(u32x4*)(qrow + 32 + 8 * fq) = wb;
.LBB0_432:
	v_mov_b32_e32 v130, v190
	s_movk_i32 s1, 0xffc0
	v_and_b32_e32 v128, 15, v130
	v_ashrrev_i32_e32 v131, 2, v130
	v_lshrrev_b32_e32 v129, 6, v130
	v_and_or_b32 v166, v131, s1, v128
	s_ashr_i32 s1, s24, 3
	v_bfi_b32 v128, 3, v129, s1
	v_ashrrev_i32_e32 v129, 31, v128
	v_lshlrev_b64 v[144:145], 13, v[128:129]
	v_lshrrev_b32_e32 v128, 1, v130
	v_pk_mul_f32 v[130:131], v[126:127], v[126:127]
	v_pk_mul_f32 v[132:133], v[124:125], v[124:125]
	v_cmp_lt_i32_e32 vcc, v200, v192
	v_pk_mov_b32 v[134:135], v[132:133], v[130:131] op_sel:[1,0]
	v_mov_b32_e32 v133, v131
	v_pk_add_f32 v[130:131], v[134:135], v[132:133]
	v_pk_mul_f32 v[132:133], v[118:119], v[118:119]
	v_pk_add_f32 v[130:131], v[130:131], v[130:131] op_sel_hi:[0,1]
	v_pk_mul_f32 v[134:135], v[116:117], v[116:117]
	v_mul_f32_e32 v130, v120, v120
	v_pk_mov_b32 v[146:147], v[134:135], v[132:133] op_sel:[1,0]
	v_mov_b32_e32 v135, v133
	v_pk_add_f32 v[132:133], v[146:147], v[134:135]
	v_pk_fma_f32 v[134:135], v[120:121], v[120:121], v[130:131] op_sel_hi:[1,1,0]
	v_mul_f32_e32 v130, v122, v122
	v_pk_add_f32 v[132:133], v[132:133], v[132:133] op_sel_hi:[0,1]
	v_pk_fma_f32 v[146:147], v[122:123], v[122:123], v[130:131] op_sel_hi:[1,1,0]
	v_mul_f32_e32 v134, v112, v112
	v_mul_f32_e32 v146, v113, v113
	v_mul_f32_e32 v132, v114, v114
	v_mul_f32_e32 v130, v115, v115
	v_pk_add_f32 v[134:135], v[134:135], v[146:147]
	v_pk_add_f32 v[130:131], v[132:133], v[130:131]
	s_mov_b32 s19, 0xf800000
	v_pk_add_f32 v[130:131], v[134:135], v[130:131]
	s_lshl_b32 s0, s24, 8
	v_add_f32_e32 v129, v130, v131
	v_cndmask_b32_e32 v130, v191, v200, vcc
	v_lshlrev_b32_e32 v158, 2, v130
	ds_bpermute_b32 v130, v158, v129
	v_cmp_lt_i32_e32 vcc, v198, v192
	s_and_b32 s0, s0, 0x1f00
	v_or_b32_e32 v144, s0, v144
	v_and_b32_e32 v149, 24, v128
	s_waitcnt lgkmcnt(0)
	v_add_f32_e32 v129, v129, v130
	v_cndmask_b32_e32 v130, v191, v198, vcc
	v_lshlrev_b32_e32 v159, 2, v130
	ds_bpermute_b32 v130, v159, v129
	v_mov_b32_e32 v128, v166
	s_ashr_i32 s25, s24, 31
	s_lshl_b64 s[24:25], s[24:25], 13
	s_waitcnt lgkmcnt(0)
	v_add_f32_e32 v129, v129, v130
	v_fmamk_f32 v129, v129, 0x3c800000, v199
	v_cmp_gt_f32_e32 vcc, s19, v129
	v_mul_f32_e32 v130, 0x4f800000, v129
	v_readlane_b32 s26, v252, 19
	v_cndmask_b32_e32 v129, v129, v130, vcc
	v_sqrt_f32_e32 v130, v129
	v_readlane_b32 s42, v252, 21
	v_readlane_b32 s27, v252, 20
	v_readlane_b32 s43, v252, 22
	v_add_u32_e32 v131, -1, v130
	v_fma_f32 v132, -v131, v130, v129
	v_cmp_ge_f32_e64 s[0:1], 0, v132
	v_add_u32_e32 v132, 1, v130
	v_mov_b64_e32 v[146:147], s[62:63]
	v_cndmask_b32_e64 v131, v130, v131, s[0:1]
	v_fma_f32 v130, -v132, v130, v129
	v_cmp_lt_f32_e64 s[0:1], 0, v130
	v_lshlrev_b32_e32 v160, 2, v149
	s_nop 0
	v_cndmask_b32_e64 v130, v131, v132, s[0:1]
	v_mul_f32_e32 v131, 0x37800000, v130
	v_cndmask_b32_e32 v130, v130, v131, vcc
	v_cmp_class_f32_e32 vcc, v129, v201
	s_nop 1
	v_cndmask_b32_e32 v129, v130, v129, vcc
	v_div_scale_f32 v130, s[0:1], v129, v129, 1.0
	v_rcp_f32_e32 v131, v130
	s_nop 0
	v_fma_f32 v132, -v130, v131, 1.0
	v_fmac_f32_e32 v131, v132, v131
	v_div_scale_f32 v132, vcc, 1.0, v129, 1.0
	v_mul_f32_e32 v133, v132, v131
	v_fma_f32 v134, -v130, v133, v132
	v_fmac_f32_e32 v133, v134, v131
	v_fma_f32 v130, -v130, v133, v132
	v_div_fmas_f32 v130, v130, v131, v133
	v_div_fixup_f32 v148, v130, v129, 1.0
	v_ashrrev_i32_e32 v129, 31, v128
	v_lshl_add_u64 v[130:131], v[144:145], 0, v[128:129]
	v_lshlrev_b64 v[128:129], 5, v[128:129]
	v_lshl_add_u64 v[128:129], v[128:129], 0, s[24:25]
	v_lshlrev_b64 v[132:133], 2, v[128:129]
	v_lshl_add_u64 v[128:129], s[26:27], 0, v[132:133]
	v_lshl_add_u64 v[132:133], s[42:43], 0, v[132:133]
	v_mad_u64_u32 v[150:151], s[0:1], v130, s67, v[146:147]
	v_lshl_add_u64 v[152:153], v[128:129], 0, v[160:161]
	v_lshl_add_u64 v[154:155], v[132:133], 0, v[160:161]
	v_mad_i32_i24 v151, v131, s67, v151
	global_load_dwordx4 v[128:131], v[152:153], off
	global_load_dwordx4 v[132:135], v[154:155], off
	global_load_dwordx4 v[162:165], v160, s[6:7]
	global_load_dwordx4 v[168:171], v160, s[6:7] offset:128
	global_load_dwordx4 v[230:233], v[152:153], off offset:16
	global_load_dwordx4 v[234:237], v[154:155], off offset:16
	global_load_dwordx4 v[238:241], v160, s[6:7] offset:16
	global_load_dwordx4 v[242:245], v160, s[6:7] offset:144
	v_pk_mul_f32 v[120:121], v[120:121], v[148:149] op_sel_hi:[1,0]
	v_pk_mul_f32 v[122:123], v[122:123], v[148:149] op_sel_hi:[1,0]
	v_pk_mul_f32 v[126:127], v[126:127], v[148:149] op_sel_hi:[1,0]
	v_pk_mul_f32 v[124:125], v[124:125], v[148:149] op_sel_hi:[1,0]
	v_pk_mul_f32 v[112:113], v[112:113], v[148:149] op_sel_hi:[1,0]
	v_pk_mul_f32 v[114:115], v[114:115], v[148:149] op_sel_hi:[1,0]
	v_pk_mul_f32 v[118:119], v[118:119], v[148:149] op_sel_hi:[1,0]
	v_pk_mul_f32 v[116:117], v[116:117], v[148:149] op_sel_hi:[1,0]
	s_waitcnt vmcnt(4)
	v_pk_mul_f32 v[124:125], v[162:163], v[124:125]
	v_pk_mul_f32 v[122:123], v[170:171], v[122:123]
	v_pk_mul_f32 v[120:121], v[168:169], v[120:121]
	v_pk_mul_f32 v[126:127], v[164:165], v[126:127]
	v_pk_mul_f32 v[162:163], v[132:133], v[120:121]
	v_pk_mul_f32 v[164:165], v[134:135], v[122:123]
	v_pk_mul_f32 v[120:121], v[128:129], v[120:121]
	v_pk_fma_f32 v[164:165], v[130:131], v[126:127], v[164:165] neg_lo:[0,0,1] neg_hi:[0,0,1]
	v_pk_fma_f32 v[162:163], v[128:129], v[124:125], v[162:163] neg_lo:[0,0,1] neg_hi:[0,0,1]
	v_pk_mul_f32 v[122:123], v[130:131], v[122:123]
	v_pk_fma_f32 v[124:125], v[132:133], v[124:125], v[120:121]
	v_pk_fma_f32 v[122:123], v[134:135], v[126:127], v[122:123]
	v_cvt_pk_bf16_f32 v120, v162, v163
	v_cvt_pk_bf16_f32 v121, v164, v165
	v_cvt_pk_bf16_f32 v124, v124, v125
	s_nop 0
	v_cvt_pk_bf16_f32 v125, v122, v123
	s_nop 0
	s_waitcnt vmcnt(1)
; __device__ __forceinline__ unsigned cvt_pk_bf16(float lo, float hi) { unsigned r; asm volatile("v_cvt_pk_bf16_f32 %0, %1, %2" : "=v"(r) : "v"(lo), "v"(hi)); return r; }
;     __device__ __forceinline__ void operator()(const f32x4 (&acc)[2][2][4][2], const Unit& u, int wr_, int wc_, int fr_, int fq_) const {
;     ...
;                 for (int m = 0; m < 4; ++m) { int rl = ai * HALF + wr * 64 + m * 16 + fr; asm volatile("" : "+v"(rl)); float s = 0.f;
; #pragma unroll
;                     for (int bj = 0; bj < 2; ++bj)
; #pragma unroll
;                         for (int n = 0; n < 2; ++n) { const f32x4 x = acc[ai][bj][m][n]; s += (x[0] * x[0] + x[1] * x[1]) + (x[2] * x[2] + x[3] * x[3]); }
;                     s += __shfl_xor(s, 16); s += __shfl_xor(s, 32);
;                     const float rr = 1.0f / sqrtf(s * (1.0f / 64.0f) + RMS_EPS_F);
;                     const size_t t = (size_t)u.pm * BM + rl;
;                     bf16_t* qrow = Q + ((size_t)(b * 4 + wc) * 8192 + s0 + rl) * 192 + 128;
;                     u32x4 wa, wb;
; #pragma unroll
;                     for (int n = 0; n < 2; ++n) { const int j0 = 8 * fq + 4 * n;
;                         const f32x4 c4 = *(const f32x4*)(cosT + t * 32 + j0), s4 = *(const f32x4*)(sinT + t * 32 + j0);
;                         const f32x4 g1 = *(const f32x4*)(gn_rope + j0), g2 = *(const f32x4*)(gn_rope + 32 + j0);
;                         const f32x4 y1 = acc[ai][0][m][n] * rr * g1, y2 = acc[ai][1][m][n] * rr * g2;
;                         const f32x4 o1 = y1 * c4 - y2 * s4, o2 = y2 * c4 + y1 * s4;
;                         wa[2 * n] = cvt_pk_bf16(o1[0], o1[1]); wa[2 * n + 1] = cvt_pk_bf16(o1[2], o1[3]); wb[2 * n] = cvt_pk_bf16(o2[0], o2[1]); wb[2 * n + 1] = cvt_pk_bf16(o2[2], o2[3]); }
;                     *(u32x4*)(qrow + 8 * fq) = wa; *(u32x4*)(qrow + 32 + 8 * fq) = wb;
;                     asm volatile("" ::: "memory"); }
	v_pk_mul_f32 v[116:117], v[116:117], v[238:239]
	s_waitcnt vmcnt(0)
	v_pk_mul_f32 v[114:115], v[114:115], v[244:245]
	v_pk_mul_f32 v[112:113], v[112:113], v[242:243]
	v_pk_mul_f32 v[118:119], v[118:119], v[240:241]
	v_pk_mul_f32 v[122:123], v[234:235], v[112:113]
	v_pk_mul_f32 v[134:135], v[236:237], v[114:115]
	v_pk_mul_f32 v[114:115], v[232:233], v[114:115]
	v_pk_fma_f32 v[122:123], v[230:231], v[116:117], v[122:123] neg_lo:[0,0,1] neg_hi:[0,0,1]
	v_pk_mul_f32 v[112:113], v[230:231], v[112:113]
	v_pk_fma_f32 v[114:115], v[236:237], v[118:119], v[114:115]
	v_pk_fma_f32 v[134:135], v[232:233], v[118:119], v[134:135] neg_lo:[0,0,1] neg_hi:[0,0,1]
	v_pk_fma_f32 v[112:113], v[234:235], v[116:117], v[112:113]
	v_cvt_pk_bf16_f32 v122, v122, v123
	v_cvt_pk_bf16_f32 v123, v134, v135
	v_pk_mul_f32 v[116:117], v[108:109], v[108:109]
	v_cvt_pk_bf16_f32 v126, v112, v113
	v_cvt_pk_bf16_f32 v127, v114, v115
	v_pk_mul_f32 v[114:115], v[110:111], v[110:111]
	v_lshlrev_b32_e32 v128, 1, v149
	v_pk_mov_b32 v[118:119], v[116:117], v[114:115] op_sel:[1,0]
	v_mov_b32_e32 v117, v115
	v_mov_b32_e32 v129, v161
	v_pk_add_f32 v[114:115], v[118:119], v[116:117]
	v_lshl_add_u64 v[112:113], v[150:151], 0, v[128:129]
	v_pk_add_f32 v[114:115], v[114:115], v[114:115] op_sel_hi:[0,1]
	v_pk_mul_f32 v[116:117], v[102:103], v[102:103]
	v_pk_mul_f32 v[118:119], v[100:101], v[100:101]
	global_store_dwordx4 v[112:113], v[120:123], off offset:256
	global_store_dwordx4 v[112:113], v[124:127], off offset:320
	v_mul_f32_e32 v114, v104, v104
	v_pk_mov_b32 v[120:121], v[118:119], v[116:117] op_sel:[1,0]
	v_mov_b32_e32 v119, v117
	v_pk_add_f32 v[116:117], v[120:121], v[118:119]
	v_pk_fma_f32 v[118:119], v[104:105], v[104:105], v[114:115] op_sel_hi:[1,1,0]
	v_mul_f32_e32 v114, v106, v106
	v_pk_add_f32 v[116:117], v[116:117], v[116:117] op_sel_hi:[0,1]
	v_pk_fma_f32 v[120:121], v[106:107], v[106:107], v[114:115] op_sel_hi:[1,1,0]
	v_mul_f32_e32 v118, v96, v96
	v_mul_f32_e32 v120, v97, v97
	v_mul_f32_e32 v116, v98, v98
	v_mul_f32_e32 v114, v99, v99
	v_pk_add_f32 v[118:119], v[118:119], v[120:121]
	v_pk_add_f32 v[114:115], v[116:117], v[114:115]
	v_or_b32_e32 v112, 16, v166
	v_pk_add_f32 v[114:115], v[118:119], v[114:115]
	s_nop 0
	v_add_f32_e32 v113, v114, v115
	ds_bpermute_b32 v114, v158, v113
	s_waitcnt lgkmcnt(0)
	v_add_f32_e32 v113, v113, v114
	ds_bpermute_b32 v114, v159, v113
	s_waitcnt lgkmcnt(0)
	v_add_f32_e32 v113, v113, v114
	v_fmamk_f32 v113, v113, 0x3c800000, v199
	v_cmp_gt_f32_e32 vcc, s19, v113
	v_mul_f32_e32 v114, 0x4f800000, v113
	s_nop 0
	v_cndmask_b32_e32 v113, v113, v114, vcc
	v_sqrt_f32_e32 v114, v113
	s_nop 0
	v_add_u32_e32 v115, -1, v114
	v_fma_f32 v116, -v115, v114, v113
	v_cmp_ge_f32_e64 s[0:1], 0, v116
	v_add_u32_e32 v116, 1, v114
	s_nop 0
	v_cndmask_b32_e64 v115, v114, v115, s[0:1]
	v_fma_f32 v114, -v116, v114, v113
	v_cmp_lt_f32_e64 s[0:1], 0, v114
	s_nop 1
	v_cndmask_b32_e64 v114, v115, v116, s[0:1]
	v_mul_f32_e32 v115, 0x37800000, v114
	v_cndmask_b32_e32 v114, v114, v115, vcc
	v_cmp_class_f32_e32 vcc, v113, v201
	s_nop 1
	v_cndmask_b32_e32 v113, v114, v113, vcc
	v_div_scale_f32 v114, s[0:1], v113, v113, 1.0
	v_rcp_f32_e32 v115, v114
	s_nop 0
	v_fma_f32 v116, -v114, v115, 1.0
	v_fmac_f32_e32 v115, v116, v115
	v_div_scale_f32 v116, vcc, 1.0, v113, 1.0
	v_mul_f32_e32 v117, v116, v115
	v_fma_f32 v118, -v114, v117, v116
	v_fmac_f32_e32 v117, v118, v115
	v_fma_f32 v114, -v114, v117, v116
	v_div_fmas_f32 v114, v114, v115, v117
	v_div_fixup_f32 v132, v114, v113, 1.0
	v_ashrrev_i32_e32 v113, 31, v112
	v_lshl_add_u64 v[114:115], v[144:145], 0, v[112:113]
	v_lshlrev_b64 v[112:113], 5, v[112:113]
	v_lshl_add_u64 v[112:113], v[112:113], 0, s[24:25]
	v_mad_u64_u32 v[130:131], s[0:1], v114, s67, v[146:147]
	v_lshlrev_b64 v[112:113], 2, v[112:113]
	v_mad_i32_i24 v131, v115, s67, v131
	v_lshl_add_u64 v[114:115], s[26:27], 0, v[112:113]
	v_lshl_add_u64 v[112:113], s[42:43], 0, v[112:113]
	v_lshl_add_u64 v[134:135], v[114:115], 0, v[160:161]
	v_lshl_add_u64 v[148:149], v[112:113], 0, v[160:161]
	global_load_dwordx4 v[116:119], v[134:135], off
	global_load_dwordx4 v[112:115], v[148:149], off
	global_load_dwordx4 v[124:127], v160, s[6:7]
	global_load_dwordx4 v[120:123], v160, s[6:7] offset:128
	global_load_dwordx4 v[230:233], v[134:135], off offset:16
	global_load_dwordx4 v[234:237], v[148:149], off offset:16
	global_load_dwordx4 v[238:241], v160, s[6:7] offset:16
	global_load_dwordx4 v[242:245], v160, s[6:7] offset:144
	v_pk_mul_f32 v[104:105], v[104:105], v[132:133] op_sel_hi:[1,0]
	v_pk_mul_f32 v[106:107], v[106:107], v[132:133] op_sel_hi:[1,0]
	v_pk_mul_f32 v[110:111], v[110:111], v[132:133] op_sel_hi:[1,0]
	v_pk_mul_f32 v[108:109], v[108:109], v[132:133] op_sel_hi:[1,0]
	v_pk_mul_f32 v[96:97], v[96:97], v[132:133] op_sel_hi:[1,0]
	v_pk_mul_f32 v[98:99], v[98:99], v[132:133] op_sel_hi:[1,0]
	v_pk_mul_f32 v[102:103], v[102:103], v[132:133] op_sel_hi:[1,0]
	v_pk_mul_f32 v[100:101], v[100:101], v[132:133] op_sel_hi:[1,0]
	s_waitcnt vmcnt(5)
	v_pk_mul_f32 v[108:109], v[124:125], v[108:109]
	s_waitcnt vmcnt(4)
	v_pk_mul_f32 v[106:107], v[122:123], v[106:107]
	v_pk_mul_f32 v[104:105], v[120:121], v[104:105]
	v_pk_mul_f32 v[110:111], v[126:127], v[110:111]
	v_pk_mul_f32 v[120:121], v[112:113], v[104:105]
	v_pk_mul_f32 v[122:123], v[114:115], v[106:107]
	v_pk_mul_f32 v[104:105], v[116:117], v[104:105]
	v_pk_fma_f32 v[122:123], v[118:119], v[110:111], v[122:123] neg_lo:[0,0,1] neg_hi:[0,0,1]
	v_pk_fma_f32 v[120:121], v[116:117], v[108:109], v[120:121] neg_lo:[0,0,1] neg_hi:[0,0,1]
	v_pk_mul_f32 v[106:107], v[118:119], v[106:107]
	v_pk_fma_f32 v[108:109], v[112:113], v[108:109], v[104:105]
	v_pk_fma_f32 v[106:107], v[114:115], v[110:111], v[106:107]
	v_cvt_pk_bf16_f32 v104, v120, v121
	v_cvt_pk_bf16_f32 v105, v122, v123
	v_cvt_pk_bf16_f32 v108, v108, v109
	s_nop 0
	v_cvt_pk_bf16_f32 v109, v106, v107
	s_waitcnt vmcnt(1)
; __device__ __forceinline__ unsigned cvt_pk_bf16(float lo, float hi) { unsigned r; asm volatile("v_cvt_pk_bf16_f32 %0, %1, %2" : "=v"(r) : "v"(lo), "v"(hi)); return r; }
;     __device__ __forceinline__ void operator()(const f32x4 (&acc)[2][2][4][2], const Unit& u, int wr_, int wc_, int fr_, int fq_) const {
;     ...
;                 for (int m = 0; m < 4; ++m) { int rl = ai * HALF + wr * 64 + m * 16 + fr; asm volatile("" : "+v"(rl)); float s = 0.f;
; #pragma unroll
;                     for (int bj = 0; bj < 2; ++bj)
; #pragma unroll
;                         for (int n = 0; n < 2; ++n) { const f32x4 x = acc[ai][bj][m][n]; s += (x[0] * x[0] + x[1] * x[1]) + (x[2] * x[2] + x[3] * x[3]); }
;                     s += __shfl_xor(s, 16); s += __shfl_xor(s, 32);
;                     const float rr = 1.0f / sqrtf(s * (1.0f / 64.0f) + RMS_EPS_F);
;                     const size_t t = (size_t)u.pm * BM + rl;
;                     bf16_t* qrow = Q + ((size_t)(b * 4 + wc) * 8192 + s0 + rl) * 192 + 128;
;                     u32x4 wa, wb;
; #pragma unroll
;                     for (int n = 0; n < 2; ++n) { const int j0 = 8 * fq + 4 * n;
;                         const f32x4 c4 = *(const f32x4*)(cosT + t * 32 + j0), s4 = *(const f32x4*)(sinT + t * 32 + j0);
;                         const f32x4 g1 = *(const f32x4*)(gn_rope + j0), g2 = *(const f32x4*)(gn_rope + 32 + j0);
;                         const f32x4 y1 = acc[ai][0][m][n] * rr * g1, y2 = acc[ai][1][m][n] * rr * g2;
;                         const f32x4 o1 = y1 * c4 - y2 * s4, o2 = y2 * c4 + y1 * s4;
;                         wa[2 * n] = cvt_pk_bf16(o1[0], o1[1]); wa[2 * n + 1] = cvt_pk_bf16(o1[2], o1[3]); wb[2 * n] = cvt_pk_bf16(o2[0], o2[1]); wb[2 * n + 1] = cvt_pk_bf16(o2[2], o2[3]); }
;                     *(u32x4*)(qrow + 8 * fq) = wa; *(u32x4*)(qrow + 32 + 8 * fq) = wb;
;                     asm volatile("" ::: "memory"); }
	v_pk_mul_f32 v[100:101], v[100:101], v[238:239]
	s_waitcnt vmcnt(0)
	v_pk_mul_f32 v[98:99], v[98:99], v[244:245]
	v_pk_mul_f32 v[96:97], v[96:97], v[242:243]
	v_pk_mul_f32 v[102:103], v[102:103], v[240:241]
	v_pk_mul_f32 v[106:107], v[234:235], v[96:97]
	v_pk_mul_f32 v[118:119], v[236:237], v[98:99]
	v_pk_mul_f32 v[98:99], v[232:233], v[98:99]
	v_pk_fma_f32 v[106:107], v[230:231], v[100:101], v[106:107] neg_lo:[0,0,1] neg_hi:[0,0,1]
	v_pk_mul_f32 v[96:97], v[230:231], v[96:97]
	v_pk_fma_f32 v[98:99], v[236:237], v[102:103], v[98:99]
	v_pk_fma_f32 v[118:119], v[232:233], v[102:103], v[118:119] neg_lo:[0,0,1] neg_hi:[0,0,1]
	v_pk_fma_f32 v[96:97], v[234:235], v[100:101], v[96:97]
	v_cvt_pk_bf16_f32 v106, v106, v107
	v_cvt_pk_bf16_f32 v107, v118, v119
	v_pk_mul_f32 v[100:101], v[92:93], v[92:93]
	v_cvt_pk_bf16_f32 v110, v96, v97
	v_cvt_pk_bf16_f32 v111, v98, v99
	v_pk_mul_f32 v[98:99], v[94:95], v[94:95]
	v_lshl_add_u64 v[96:97], v[130:131], 0, v[128:129]
	v_pk_mov_b32 v[102:103], v[100:101], v[98:99] op_sel:[1,0]
	v_mov_b32_e32 v101, v99
	v_pk_add_f32 v[98:99], v[102:103], v[100:101]
	v_pk_mul_f32 v[100:101], v[86:87], v[86:87]
	v_pk_add_f32 v[98:99], v[98:99], v[98:99] op_sel_hi:[0,1]
	v_pk_mul_f32 v[102:103], v[84:85], v[84:85]
	global_store_dwordx4 v[96:97], v[104:107], off offset:256
	global_store_dwordx4 v[96:97], v[108:111], off offset:320
	v_mul_f32_e32 v98, v88, v88
	v_pk_mov_b32 v[104:105], v[102:103], v[100:101] op_sel:[1,0]
	v_mov_b32_e32 v103, v101
	v_pk_add_f32 v[100:101], v[104:105], v[102:103]
	v_pk_fma_f32 v[102:103], v[88:89], v[88:89], v[98:99] op_sel_hi:[1,1,0]
	v_mul_f32_e32 v98, v90, v90
	v_pk_add_f32 v[100:101], v[100:101], v[100:101] op_sel_hi:[0,1]
	v_pk_fma_f32 v[104:105], v[90:91], v[90:91], v[98:99] op_sel_hi:[1,1,0]
	v_mul_f32_e32 v102, v80, v80
	v_mul_f32_e32 v104, v81, v81
	v_mul_f32_e32 v100, v82, v82
	v_mul_f32_e32 v98, v83, v83
	v_pk_add_f32 v[102:103], v[102:103], v[104:105]
	v_pk_add_f32 v[98:99], v[100:101], v[98:99]
	v_or_b32_e32 v96, 32, v166
	v_pk_add_f32 v[98:99], v[102:103], v[98:99]
	s_nop 0
	v_add_f32_e32 v97, v98, v99
	ds_bpermute_b32 v98, v158, v97
	s_waitcnt lgkmcnt(0)
	v_add_f32_e32 v97, v97, v98
	ds_bpermute_b32 v98, v159, v97
	s_waitcnt lgkmcnt(0)
	v_add_f32_e32 v97, v97, v98
	v_fmamk_f32 v97, v97, 0x3c800000, v199
	v_cmp_gt_f32_e32 vcc, s19, v97
	v_mul_f32_e32 v98, 0x4f800000, v97
	s_nop 0
	v_cndmask_b32_e32 v97, v97, v98, vcc
	v_sqrt_f32_e32 v98, v97
	s_nop 0
	v_add_u32_e32 v99, -1, v98
	v_fma_f32 v100, -v99, v98, v97
	v_cmp_ge_f32_e64 s[0:1], 0, v100
	v_add_u32_e32 v100, 1, v98
	s_nop 0
	v_cndmask_b32_e64 v99, v98, v99, s[0:1]
	v_fma_f32 v98, -v100, v98, v97
	v_cmp_lt_f32_e64 s[0:1], 0, v98
	s_nop 1
	v_cndmask_b32_e64 v98, v99, v100, s[0:1]
	v_mul_f32_e32 v99, 0x37800000, v98
	v_cndmask_b32_e32 v98, v98, v99, vcc
	v_cmp_class_f32_e32 vcc, v97, v201
	s_nop 1
	v_cndmask_b32_e32 v97, v98, v97, vcc
	v_div_scale_f32 v98, s[0:1], v97, v97, 1.0
	v_rcp_f32_e32 v99, v98
	s_nop 0
	v_fma_f32 v100, -v98, v99, 1.0
	v_fmac_f32_e32 v99, v100, v99
	v_div_scale_f32 v100, vcc, 1.0, v97, 1.0
	v_mul_f32_e32 v101, v100, v99
	v_fma_f32 v102, -v98, v101, v100
	v_fmac_f32_e32 v101, v102, v99
	v_fma_f32 v98, -v98, v101, v100
	v_div_fmas_f32 v98, v98, v99, v101
	v_div_fixup_f32 v114, v98, v97, 1.0
	v_ashrrev_i32_e32 v97, 31, v96
	v_lshl_add_u64 v[98:99], v[144:145], 0, v[96:97]
	v_lshlrev_b64 v[96:97], 5, v[96:97]
	v_lshl_add_u64 v[96:97], v[96:97], 0, s[24:25]
	v_mad_u64_u32 v[112:113], s[0:1], v98, s67, v[146:147]
	v_lshlrev_b64 v[96:97], 2, v[96:97]
	v_mad_i32_i24 v113, v99, s67, v113
	v_lshl_add_u64 v[98:99], s[26:27], 0, v[96:97]
	v_lshl_add_u64 v[96:97], s[42:43], 0, v[96:97]
	v_lshl_add_u64 v[116:117], v[98:99], 0, v[160:161]
	v_lshl_add_u64 v[118:119], v[96:97], 0, v[160:161]
	global_load_dwordx4 v[100:103], v[116:117], off
	global_load_dwordx4 v[96:99], v[118:119], off
	global_load_dwordx4 v[108:111], v160, s[6:7]
	global_load_dwordx4 v[104:107], v160, s[6:7] offset:128
	global_load_dwordx4 v[230:233], v[116:117], off offset:16
	global_load_dwordx4 v[234:237], v[118:119], off offset:16
	global_load_dwordx4 v[238:241], v160, s[6:7] offset:16
	global_load_dwordx4 v[242:245], v160, s[6:7] offset:144
	v_pk_mul_f32 v[88:89], v[88:89], v[114:115] op_sel_hi:[1,0]
	v_pk_mul_f32 v[90:91], v[90:91], v[114:115] op_sel_hi:[1,0]
	v_pk_mul_f32 v[94:95], v[94:95], v[114:115] op_sel_hi:[1,0]
	v_pk_mul_f32 v[92:93], v[92:93], v[114:115] op_sel_hi:[1,0]
	v_pk_mul_f32 v[80:81], v[80:81], v[114:115] op_sel_hi:[1,0]
	v_pk_mul_f32 v[82:83], v[82:83], v[114:115] op_sel_hi:[1,0]
	v_pk_mul_f32 v[86:87], v[86:87], v[114:115] op_sel_hi:[1,0]
	v_pk_mul_f32 v[84:85], v[84:85], v[114:115] op_sel_hi:[1,0]
	s_waitcnt vmcnt(5)
	v_pk_mul_f32 v[92:93], v[108:109], v[92:93]
	s_waitcnt vmcnt(4)
	v_pk_mul_f32 v[90:91], v[106:107], v[90:91]
	v_pk_mul_f32 v[88:89], v[104:105], v[88:89]
	v_pk_mul_f32 v[94:95], v[110:111], v[94:95]
	v_pk_mul_f32 v[104:105], v[96:97], v[88:89]
	v_pk_mul_f32 v[106:107], v[98:99], v[90:91]
	v_pk_mul_f32 v[88:89], v[100:101], v[88:89]
	v_pk_fma_f32 v[106:107], v[102:103], v[94:95], v[106:107] neg_lo:[0,0,1] neg_hi:[0,0,1]
	v_pk_fma_f32 v[104:105], v[100:101], v[92:93], v[104:105] neg_lo:[0,0,1] neg_hi:[0,0,1]
	v_pk_mul_f32 v[90:91], v[102:103], v[90:91]
	v_pk_fma_f32 v[92:93], v[96:97], v[92:93], v[88:89]
	v_pk_fma_f32 v[90:91], v[98:99], v[94:95], v[90:91]
	v_cvt_pk_bf16_f32 v88, v104, v105
	v_cvt_pk_bf16_f32 v89, v106, v107
	v_cvt_pk_bf16_f32 v92, v92, v93
	s_nop 0
	v_cvt_pk_bf16_f32 v93, v90, v91
	s_waitcnt vmcnt(1)
	v_pk_mul_f32 v[84:85], v[84:85], v[238:239]
	s_waitcnt vmcnt(0)
; __device__ __forceinline__ unsigned cvt_pk_bf16(float lo, float hi) { unsigned r; asm volatile("v_cvt_pk_bf16_f32 %0, %1, %2" : "=v"(r) : "v"(lo), "v"(hi)); return r; }
;     __device__ __forceinline__ void operator()(const f32x4 (&acc)[2][2][4][2], const Unit& u, int wr_, int wc_, int fr_, int fq_) const {
;     ...
;                 for (int m = 0; m < 4; ++m) { int rl = ai * HALF + wr * 64 + m * 16 + fr; asm volatile("" : "+v"(rl)); float s = 0.f;
; #pragma unroll
;                     for (int bj = 0; bj < 2; ++bj)
; #pragma unroll
;                         for (int n = 0; n < 2; ++n) { const f32x4 x = acc[ai][bj][m][n]; s += (x[0] * x[0] + x[1] * x[1]) + (x[2] * x[2] + x[3] * x[3]); }
;                     s += __shfl_xor(s, 16); s += __shfl_xor(s, 32);
;                     const float rr = 1.0f / sqrtf(s * (1.0f / 64.0f) + RMS_EPS_F);
;                     const size_t t = (size_t)u.pm * BM + rl;
;                     bf16_t* qrow = Q + ((size_t)(b * 4 + wc) * 8192 + s0 + rl) * 192 + 128;
;                     u32x4 wa, wb;
; #pragma unroll
;                     for (int n = 0; n < 2; ++n) { const int j0 = 8 * fq + 4 * n;
;                         const f32x4 c4 = *(const f32x4*)(cosT + t * 32 + j0), s4 = *(const f32x4*)(sinT + t * 32 + j0);
;                         const f32x4 g1 = *(const f32x4*)(gn_rope + j0), g2 = *(const f32x4*)(gn_rope + 32 + j0);
;                         const f32x4 y1 = acc[ai][0][m][n] * rr * g1, y2 = acc[ai][1][m][n] * rr * g2;
;                         const f32x4 o1 = y1 * c4 - y2 * s4, o2 = y2 * c4 + y1 * s4;
;                         wa[2 * n] = cvt_pk_bf16(o1[0], o1[1]); wa[2 * n + 1] = cvt_pk_bf16(o1[2], o1[3]); wb[2 * n] = cvt_pk_bf16(o2[0], o2[1]); wb[2 * n + 1] = cvt_pk_bf16(o2[2], o2[3]); }
;                     *(u32x4*)(qrow + 8 * fq) = wa; *(u32x4*)(qrow + 32 + 8 * fq) = wb;
;                     asm volatile("" ::: "memory"); }
	v_pk_mul_f32 v[82:83], v[82:83], v[244:245]
	v_pk_mul_f32 v[80:81], v[80:81], v[242:243]
	v_pk_mul_f32 v[86:87], v[86:87], v[240:241]
	v_pk_mul_f32 v[90:91], v[234:235], v[80:81]
	v_pk_mul_f32 v[102:103], v[236:237], v[82:83]
	v_pk_mul_f32 v[82:83], v[232:233], v[82:83]
	v_pk_fma_f32 v[90:91], v[230:231], v[84:85], v[90:91] neg_lo:[0,0,1] neg_hi:[0,0,1]
	v_pk_mul_f32 v[80:81], v[230:231], v[80:81]
	v_pk_fma_f32 v[82:83], v[236:237], v[86:87], v[82:83]
	v_pk_fma_f32 v[102:103], v[232:233], v[86:87], v[102:103] neg_lo:[0,0,1] neg_hi:[0,0,1]
	v_pk_fma_f32 v[80:81], v[234:235], v[84:85], v[80:81]
	v_cvt_pk_bf16_f32 v90, v90, v91
	v_cvt_pk_bf16_f32 v91, v102, v103
	v_pk_mul_f32 v[84:85], v[76:77], v[76:77]
	v_cvt_pk_bf16_f32 v94, v80, v81
	v_cvt_pk_bf16_f32 v95, v82, v83
	v_pk_mul_f32 v[82:83], v[78:79], v[78:79]
	v_lshl_add_u64 v[80:81], v[112:113], 0, v[128:129]
	v_pk_mov_b32 v[86:87], v[84:85], v[82:83] op_sel:[1,0]
	v_mov_b32_e32 v85, v83
	v_pk_add_f32 v[82:83], v[86:87], v[84:85]
	v_pk_mul_f32 v[84:85], v[70:71], v[70:71]
	v_pk_add_f32 v[82:83], v[82:83], v[82:83] op_sel_hi:[0,1]
	v_pk_mul_f32 v[86:87], v[68:69], v[68:69]
	global_store_dwordx4 v[80:81], v[88:91], off offset:256
	global_store_dwordx4 v[80:81], v[92:95], off offset:320
	v_mul_f32_e32 v82, v72, v72
	v_pk_mov_b32 v[88:89], v[86:87], v[84:85] op_sel:[1,0]
	v_mov_b32_e32 v87, v85
	v_pk_add_f32 v[84:85], v[88:89], v[86:87]
	v_pk_fma_f32 v[86:87], v[72:73], v[72:73], v[82:83] op_sel_hi:[1,1,0]
	v_mul_f32_e32 v82, v74, v74
	v_pk_add_f32 v[84:85], v[84:85], v[84:85] op_sel_hi:[0,1]
	v_pk_fma_f32 v[88:89], v[74:75], v[74:75], v[82:83] op_sel_hi:[1,1,0]
	v_mul_f32_e32 v86, v64, v64
	v_mul_f32_e32 v88, v65, v65
	v_mul_f32_e32 v84, v66, v66
	v_mul_f32_e32 v82, v67, v67
	v_pk_add_f32 v[86:87], v[86:87], v[88:89]
	v_pk_add_f32 v[82:83], v[84:85], v[82:83]
	v_or_b32_e32 v80, 48, v166
	v_pk_add_f32 v[82:83], v[86:87], v[82:83]
	s_nop 0
	v_add_f32_e32 v81, v82, v83
	ds_bpermute_b32 v82, v158, v81
	s_waitcnt lgkmcnt(0)
	v_add_f32_e32 v81, v81, v82
	ds_bpermute_b32 v82, v159, v81
	s_waitcnt lgkmcnt(0)
	v_add_f32_e32 v81, v81, v82
	v_fmamk_f32 v81, v81, 0x3c800000, v199
	v_cmp_gt_f32_e32 vcc, s19, v81
	v_mul_f32_e32 v82, 0x4f800000, v81
	s_nop 0
	v_cndmask_b32_e32 v81, v81, v82, vcc
	v_sqrt_f32_e32 v82, v81
	s_nop 0
	v_add_u32_e32 v83, -1, v82
	v_fma_f32 v84, -v83, v82, v81
	v_cmp_ge_f32_e64 s[0:1], 0, v84
	v_add_u32_e32 v84, 1, v82
	s_nop 0
	v_cndmask_b32_e64 v83, v82, v83, s[0:1]
	v_fma_f32 v82, -v84, v82, v81
	v_cmp_lt_f32_e64 s[0:1], 0, v82
	s_nop 1
	v_cndmask_b32_e64 v82, v83, v84, s[0:1]
	v_mul_f32_e32 v83, 0x37800000, v82
	v_cndmask_b32_e32 v82, v82, v83, vcc
	v_cmp_class_f32_e32 vcc, v81, v201
	s_nop 1
	v_cndmask_b32_e32 v81, v82, v81, vcc
	v_div_scale_f32 v82, s[0:1], v81, v81, 1.0
	v_rcp_f32_e32 v83, v82
	s_nop 0
	v_fma_f32 v84, -v82, v83, 1.0
	v_fmac_f32_e32 v83, v84, v83
	v_div_scale_f32 v84, vcc, 1.0, v81, 1.0
	v_mul_f32_e32 v85, v84, v83
	v_fma_f32 v86, -v82, v85, v84
	v_fmac_f32_e32 v85, v86, v83
	v_fma_f32 v82, -v82, v85, v84
	v_div_fmas_f32 v82, v82, v83, v85
	v_div_fixup_f32 v98, v82, v81, 1.0
	v_ashrrev_i32_e32 v81, 31, v80
	v_lshl_add_u64 v[82:83], v[144:145], 0, v[80:81]
	v_lshlrev_b64 v[80:81], 5, v[80:81]
	v_lshl_add_u64 v[80:81], v[80:81], 0, s[24:25]
	v_mad_u64_u32 v[96:97], s[0:1], v82, s67, v[146:147]
	v_lshlrev_b64 v[80:81], 2, v[80:81]
	v_mad_i32_i24 v97, v83, s67, v97
	v_lshl_add_u64 v[82:83], s[26:27], 0, v[80:81]
	v_lshl_add_u64 v[80:81], s[42:43], 0, v[80:81]
	v_lshl_add_u64 v[100:101], v[82:83], 0, v[160:161]
	v_lshl_add_u64 v[102:103], v[80:81], 0, v[160:161]
	global_load_dwordx4 v[84:87], v[100:101], off
	global_load_dwordx4 v[80:83], v[102:103], off
	global_load_dwordx4 v[92:95], v160, s[6:7]
	global_load_dwordx4 v[88:91], v160, s[6:7] offset:128
	global_load_dwordx4 v[230:233], v[100:101], off offset:16
	global_load_dwordx4 v[234:237], v[102:103], off offset:16
	global_load_dwordx4 v[238:241], v160, s[6:7] offset:16
	global_load_dwordx4 v[242:245], v160, s[6:7] offset:144
	v_pk_mul_f32 v[72:73], v[72:73], v[98:99] op_sel_hi:[1,0]
	v_pk_mul_f32 v[74:75], v[74:75], v[98:99] op_sel_hi:[1,0]
	v_pk_mul_f32 v[78:79], v[78:79], v[98:99] op_sel_hi:[1,0]
	v_pk_mul_f32 v[76:77], v[76:77], v[98:99] op_sel_hi:[1,0]
	v_pk_mul_f32 v[64:65], v[64:65], v[98:99] op_sel_hi:[1,0]
	v_pk_mul_f32 v[66:67], v[66:67], v[98:99] op_sel_hi:[1,0]
	v_pk_mul_f32 v[70:71], v[70:71], v[98:99] op_sel_hi:[1,0]
	v_pk_mul_f32 v[68:69], v[68:69], v[98:99] op_sel_hi:[1,0]
	s_waitcnt vmcnt(5)
	v_pk_mul_f32 v[76:77], v[92:93], v[76:77]
	s_waitcnt vmcnt(4)
	v_pk_mul_f32 v[74:75], v[90:91], v[74:75]
	v_pk_mul_f32 v[72:73], v[88:89], v[72:73]
	v_pk_mul_f32 v[78:79], v[94:95], v[78:79]
	v_pk_mul_f32 v[88:89], v[80:81], v[72:73]
	v_pk_mul_f32 v[90:91], v[82:83], v[74:75]
	v_pk_mul_f32 v[72:73], v[84:85], v[72:73]
	v_pk_fma_f32 v[90:91], v[86:87], v[78:79], v[90:91] neg_lo:[0,0,1] neg_hi:[0,0,1]
	v_pk_fma_f32 v[88:89], v[84:85], v[76:77], v[88:89] neg_lo:[0,0,1] neg_hi:[0,0,1]
	v_pk_mul_f32 v[74:75], v[86:87], v[74:75]
	v_pk_fma_f32 v[76:77], v[80:81], v[76:77], v[72:73]
	v_pk_fma_f32 v[74:75], v[82:83], v[78:79], v[74:75]
	v_cvt_pk_bf16_f32 v72, v88, v89
	v_cvt_pk_bf16_f32 v73, v90, v91
	v_cvt_pk_bf16_f32 v76, v76, v77
	s_nop 0
	v_cvt_pk_bf16_f32 v77, v74, v75
	s_waitcnt vmcnt(1)
	v_pk_mul_f32 v[68:69], v[68:69], v[238:239]
	s_waitcnt vmcnt(0)
; __device__ __forceinline__ unsigned cvt_pk_bf16(float lo, float hi) { unsigned r; asm volatile("v_cvt_pk_bf16_f32 %0, %1, %2" : "=v"(r) : "v"(lo), "v"(hi)); return r; }
;     __device__ __forceinline__ void operator()(const f32x4 (&acc)[2][2][4][2], const Unit& u, int wr_, int wc_, int fr_, int fq_) const {
;     ...
;                 for (int m = 0; m < 4; ++m) { int rl = ai * HALF + wr * 64 + m * 16 + fr; asm volatile("" : "+v"(rl)); float s = 0.f;
; #pragma unroll
;                     for (int bj = 0; bj < 2; ++bj)
; #pragma unroll
;                         for (int n = 0; n < 2; ++n) { const f32x4 x = acc[ai][bj][m][n]; s += (x[0] * x[0] + x[1] * x[1]) + (x[2] * x[2] + x[3] * x[3]); }
;                     s += __shfl_xor(s, 16); s += __shfl_xor(s, 32);
;                     const float rr = 1.0f / sqrtf(s * (1.0f / 64.0f) + RMS_EPS_F);
;                     const size_t t = (size_t)u.pm * BM + rl;
;                     bf16_t* qrow = Q + ((size_t)(b * 4 + wc) * 8192 + s0 + rl) * 192 + 128;
;                     u32x4 wa, wb;
; #pragma unroll
;                     for (int n = 0; n < 2; ++n) { const int j0 = 8 * fq + 4 * n;
;                         const f32x4 c4 = *(const f32x4*)(cosT + t * 32 + j0), s4 = *(const f32x4*)(sinT + t * 32 + j0);
;                         const f32x4 g1 = *(const f32x4*)(gn_rope + j0), g2 = *(const f32x4*)(gn_rope + 32 + j0);
;                         const f32x4 y1 = acc[ai][0][m][n] * rr * g1, y2 = acc[ai][1][m][n] * rr * g2;
;                         const f32x4 o1 = y1 * c4 - y2 * s4, o2 = y2 * c4 + y1 * s4;
;                         wa[2 * n] = cvt_pk_bf16(o1[0], o1[1]); wa[2 * n + 1] = cvt_pk_bf16(o1[2], o1[3]); wb[2 * n] = cvt_pk_bf16(o2[0], o2[1]); wb[2 * n + 1] = cvt_pk_bf16(o2[2], o2[3]); }
;                     *(u32x4*)(qrow + 8 * fq) = wa; *(u32x4*)(qrow + 32 + 8 * fq) = wb;
;                     asm volatile("" ::: "memory"); }
	v_pk_mul_f32 v[66:67], v[66:67], v[244:245]
	v_pk_mul_f32 v[64:65], v[64:65], v[242:243]
	v_pk_mul_f32 v[70:71], v[70:71], v[240:241]
	v_pk_mul_f32 v[74:75], v[234:235], v[64:65]
	v_pk_mul_f32 v[86:87], v[236:237], v[66:67]
	v_pk_mul_f32 v[66:67], v[232:233], v[66:67]
	v_pk_fma_f32 v[74:75], v[230:231], v[68:69], v[74:75] neg_lo:[0,0,1] neg_hi:[0,0,1]
	v_pk_mul_f32 v[64:65], v[230:231], v[64:65]
	v_pk_fma_f32 v[66:67], v[236:237], v[70:71], v[66:67]
	v_pk_fma_f32 v[86:87], v[232:233], v[70:71], v[86:87] neg_lo:[0,0,1] neg_hi:[0,0,1]
	v_pk_fma_f32 v[64:65], v[234:235], v[68:69], v[64:65]
	v_cvt_pk_bf16_f32 v74, v74, v75
	v_cvt_pk_bf16_f32 v75, v86, v87
	v_pk_mul_f32 v[68:69], v[60:61], v[60:61]
	v_cvt_pk_bf16_f32 v78, v64, v65
	v_cvt_pk_bf16_f32 v79, v66, v67
	v_pk_mul_f32 v[66:67], v[62:63], v[62:63]
	v_lshl_add_u64 v[64:65], v[96:97], 0, v[128:129]
	v_pk_mov_b32 v[70:71], v[68:69], v[66:67] op_sel:[1,0]
	v_mov_b32_e32 v69, v67
	v_pk_add_f32 v[66:67], v[70:71], v[68:69]
	v_pk_mul_f32 v[68:69], v[54:55], v[54:55]
	v_pk_add_f32 v[66:67], v[66:67], v[66:67] op_sel_hi:[0,1]
	v_pk_mul_f32 v[70:71], v[52:53], v[52:53]
	global_store_dwordx4 v[64:65], v[72:75], off offset:256
	global_store_dwordx4 v[64:65], v[76:79], off offset:320
	v_mul_f32_e32 v66, v56, v56
	v_pk_mov_b32 v[72:73], v[70:71], v[68:69] op_sel:[1,0]
	v_mov_b32_e32 v71, v69
	v_pk_add_f32 v[68:69], v[72:73], v[70:71]
	v_pk_fma_f32 v[70:71], v[56:57], v[56:57], v[66:67] op_sel_hi:[1,1,0]
	v_mul_f32_e32 v66, v58, v58
	v_pk_add_f32 v[68:69], v[68:69], v[68:69] op_sel_hi:[0,1]
	v_pk_fma_f32 v[72:73], v[58:59], v[58:59], v[66:67] op_sel_hi:[1,1,0]
	v_mul_f32_e32 v70, v48, v48
	v_mul_f32_e32 v72, v49, v49
	v_mul_f32_e32 v68, v50, v50
	v_mul_f32_e32 v66, v51, v51
	v_pk_add_f32 v[70:71], v[70:71], v[72:73]
	v_pk_add_f32 v[66:67], v[68:69], v[66:67]
	v_add_u32_e32 v64, 0x80, v166
	v_pk_add_f32 v[66:67], v[70:71], v[66:67]
	s_nop 0
	v_add_f32_e32 v65, v66, v67
	ds_bpermute_b32 v66, v158, v65
	s_waitcnt lgkmcnt(0)
	v_add_f32_e32 v65, v65, v66
	ds_bpermute_b32 v66, v159, v65
	s_waitcnt lgkmcnt(0)
	v_add_f32_e32 v65, v65, v66
	v_fmamk_f32 v65, v65, 0x3c800000, v199
	v_cmp_gt_f32_e32 vcc, s19, v65
	v_mul_f32_e32 v66, 0x4f800000, v65
	s_nop 0
	v_cndmask_b32_e32 v65, v65, v66, vcc
	v_sqrt_f32_e32 v66, v65
	s_nop 0
	v_add_u32_e32 v67, -1, v66
	v_fma_f32 v68, -v67, v66, v65
	v_cmp_ge_f32_e64 s[0:1], 0, v68
	v_add_u32_e32 v68, 1, v66
	s_nop 0
	v_cndmask_b32_e64 v67, v66, v67, s[0:1]
	v_fma_f32 v66, -v68, v66, v65
	v_cmp_lt_f32_e64 s[0:1], 0, v66
	s_nop 1
	v_cndmask_b32_e64 v66, v67, v68, s[0:1]
	v_mul_f32_e32 v67, 0x37800000, v66
	v_cndmask_b32_e32 v66, v66, v67, vcc
	v_cmp_class_f32_e32 vcc, v65, v201
	s_nop 1
	v_cndmask_b32_e32 v65, v66, v65, vcc
	v_div_scale_f32 v66, s[0:1], v65, v65, 1.0
	v_rcp_f32_e32 v67, v66
	s_nop 0
	v_fma_f32 v68, -v66, v67, 1.0
	v_fmac_f32_e32 v67, v68, v67
	v_div_scale_f32 v68, vcc, 1.0, v65, 1.0
	v_mul_f32_e32 v69, v68, v67
	v_fma_f32 v70, -v66, v69, v68
	v_fmac_f32_e32 v69, v70, v67
	v_fma_f32 v66, -v66, v69, v68
	v_div_fmas_f32 v66, v66, v67, v69
	v_div_fixup_f32 v82, v66, v65, 1.0
	v_ashrrev_i32_e32 v65, 31, v64
	v_lshl_add_u64 v[66:67], v[144:145], 0, v[64:65]
	v_lshlrev_b64 v[64:65], 5, v[64:65]
	v_lshl_add_u64 v[64:65], v[64:65], 0, s[24:25]
	v_mad_u64_u32 v[80:81], s[0:1], v66, s67, v[146:147]
	v_lshlrev_b64 v[64:65], 2, v[64:65]
	v_mad_i32_i24 v81, v67, s67, v81
	v_lshl_add_u64 v[66:67], s[26:27], 0, v[64:65]
	v_lshl_add_u64 v[64:65], s[42:43], 0, v[64:65]
	v_lshl_add_u64 v[84:85], v[66:67], 0, v[160:161]
	v_lshl_add_u64 v[86:87], v[64:65], 0, v[160:161]
	global_load_dwordx4 v[68:71], v[84:85], off
	global_load_dwordx4 v[64:67], v[86:87], off
	global_load_dwordx4 v[76:79], v160, s[6:7]
	global_load_dwordx4 v[72:75], v160, s[6:7] offset:128
	global_load_dwordx4 v[230:233], v[84:85], off offset:16
	global_load_dwordx4 v[234:237], v[86:87], off offset:16
	global_load_dwordx4 v[238:241], v160, s[6:7] offset:16
	global_load_dwordx4 v[242:245], v160, s[6:7] offset:144
	v_pk_mul_f32 v[56:57], v[56:57], v[82:83] op_sel_hi:[1,0]
	v_pk_mul_f32 v[58:59], v[58:59], v[82:83] op_sel_hi:[1,0]
	v_pk_mul_f32 v[62:63], v[62:63], v[82:83] op_sel_hi:[1,0]
	v_pk_mul_f32 v[60:61], v[60:61], v[82:83] op_sel_hi:[1,0]
	v_pk_mul_f32 v[48:49], v[48:49], v[82:83] op_sel_hi:[1,0]
	v_pk_mul_f32 v[50:51], v[50:51], v[82:83] op_sel_hi:[1,0]
	v_pk_mul_f32 v[54:55], v[54:55], v[82:83] op_sel_hi:[1,0]
	v_pk_mul_f32 v[52:53], v[52:53], v[82:83] op_sel_hi:[1,0]
	s_waitcnt vmcnt(5)
	v_pk_mul_f32 v[60:61], v[76:77], v[60:61]
	s_waitcnt vmcnt(4)
	v_pk_mul_f32 v[58:59], v[74:75], v[58:59]
	v_pk_mul_f32 v[56:57], v[72:73], v[56:57]
	v_pk_mul_f32 v[62:63], v[78:79], v[62:63]
	v_pk_mul_f32 v[72:73], v[64:65], v[56:57]
	v_pk_mul_f32 v[74:75], v[66:67], v[58:59]
	v_pk_mul_f32 v[56:57], v[68:69], v[56:57]
	v_pk_fma_f32 v[74:75], v[70:71], v[62:63], v[74:75] neg_lo:[0,0,1] neg_hi:[0,0,1]
	v_pk_fma_f32 v[72:73], v[68:69], v[60:61], v[72:73] neg_lo:[0,0,1] neg_hi:[0,0,1]
	v_pk_mul_f32 v[58:59], v[70:71], v[58:59]
	v_pk_fma_f32 v[60:61], v[64:65], v[60:61], v[56:57]
	v_pk_fma_f32 v[58:59], v[66:67], v[62:63], v[58:59]
	v_cvt_pk_bf16_f32 v56, v72, v73
	v_cvt_pk_bf16_f32 v57, v74, v75
	v_cvt_pk_bf16_f32 v60, v60, v61
	s_nop 0
	v_cvt_pk_bf16_f32 v61, v58, v59
	s_waitcnt vmcnt(1)
	v_pk_mul_f32 v[52:53], v[52:53], v[238:239]
	s_waitcnt vmcnt(0)
; __device__ __forceinline__ unsigned cvt_pk_bf16(float lo, float hi) { unsigned r; asm volatile("v_cvt_pk_bf16_f32 %0, %1, %2" : "=v"(r) : "v"(lo), "v"(hi)); return r; }
;     __device__ __forceinline__ void operator()(const f32x4 (&acc)[2][2][4][2], const Unit& u, int wr_, int wc_, int fr_, int fq_) const {
;     ...
;                 for (int m = 0; m < 4; ++m) { int rl = ai * HALF + wr * 64 + m * 16 + fr; asm volatile("" : "+v"(rl)); float s = 0.f;
; #pragma unroll
;                     for (int bj = 0; bj < 2; ++bj)
; #pragma unroll
;                         for (int n = 0; n < 2; ++n) { const f32x4 x = acc[ai][bj][m][n]; s += (x[0] * x[0] + x[1] * x[1]) + (x[2] * x[2] + x[3] * x[3]); }
;                     s += __shfl_xor(s, 16); s += __shfl_xor(s, 32);
;                     const float rr = 1.0f / sqrtf(s * (1.0f / 64.0f) + RMS_EPS_F);
;                     const size_t t = (size_t)u.pm * BM + rl;
;                     bf16_t* qrow = Q + ((size_t)(b * 4 + wc) * 8192 + s0 + rl) * 192 + 128;
;                     u32x4 wa, wb;
; #pragma unroll
;                     for (int n = 0; n < 2; ++n) { const int j0 = 8 * fq + 4 * n;
;                         const f32x4 c4 = *(const f32x4*)(cosT + t * 32 + j0), s4 = *(const f32x4*)(sinT + t * 32 + j0);
;                         const f32x4 g1 = *(const f32x4*)(gn_rope + j0), g2 = *(const f32x4*)(gn_rope + 32 + j0);
;                         const f32x4 y1 = acc[ai][0][m][n] * rr * g1, y2 = acc[ai][1][m][n] * rr * g2;
;                         const f32x4 o1 = y1 * c4 - y2 * s4, o2 = y2 * c4 + y1 * s4;
;                         wa[2 * n] = cvt_pk_bf16(o1[0], o1[1]); wa[2 * n + 1] = cvt_pk_bf16(o1[2], o1[3]); wb[2 * n] = cvt_pk_bf16(o2[0], o2[1]); wb[2 * n + 1] = cvt_pk_bf16(o2[2], o2[3]); }
;                     *(u32x4*)(qrow + 8 * fq) = wa; *(u32x4*)(qrow + 32 + 8 * fq) = wb;
;                     asm volatile("" ::: "memory"); }
	v_pk_mul_f32 v[50:51], v[50:51], v[244:245]
	v_pk_mul_f32 v[48:49], v[48:49], v[242:243]
	v_pk_mul_f32 v[54:55], v[54:55], v[240:241]
	v_pk_mul_f32 v[58:59], v[234:235], v[48:49]
	v_pk_mul_f32 v[70:71], v[236:237], v[50:51]
	v_pk_mul_f32 v[50:51], v[232:233], v[50:51]
	v_pk_fma_f32 v[58:59], v[230:231], v[52:53], v[58:59] neg_lo:[0,0,1] neg_hi:[0,0,1]
	v_pk_mul_f32 v[48:49], v[230:231], v[48:49]
	v_pk_fma_f32 v[50:51], v[236:237], v[54:55], v[50:51]
	v_pk_fma_f32 v[70:71], v[232:233], v[54:55], v[70:71] neg_lo:[0,0,1] neg_hi:[0,0,1]
	v_pk_fma_f32 v[48:49], v[234:235], v[52:53], v[48:49]
	v_cvt_pk_bf16_f32 v58, v58, v59
	v_cvt_pk_bf16_f32 v59, v70, v71
	v_pk_mul_f32 v[52:53], v[44:45], v[44:45]
	v_cvt_pk_bf16_f32 v62, v48, v49
	v_cvt_pk_bf16_f32 v63, v50, v51
	v_pk_mul_f32 v[50:51], v[46:47], v[46:47]
	v_lshl_add_u64 v[48:49], v[80:81], 0, v[128:129]
	v_pk_mov_b32 v[54:55], v[52:53], v[50:51] op_sel:[1,0]
	v_mov_b32_e32 v53, v51
	v_pk_add_f32 v[50:51], v[54:55], v[52:53]
	v_pk_mul_f32 v[52:53], v[38:39], v[38:39]
	v_pk_add_f32 v[50:51], v[50:51], v[50:51] op_sel_hi:[0,1]
	v_pk_mul_f32 v[54:55], v[36:37], v[36:37]
	global_store_dwordx4 v[48:49], v[56:59], off offset:256
	global_store_dwordx4 v[48:49], v[60:63], off offset:320
	v_mul_f32_e32 v50, v40, v40
	v_pk_mov_b32 v[56:57], v[54:55], v[52:53] op_sel:[1,0]
	v_mov_b32_e32 v55, v53
	v_pk_add_f32 v[52:53], v[56:57], v[54:55]
	v_pk_fma_f32 v[54:55], v[40:41], v[40:41], v[50:51] op_sel_hi:[1,1,0]
	v_mul_f32_e32 v50, v42, v42
	v_pk_add_f32 v[52:53], v[52:53], v[52:53] op_sel_hi:[0,1]
	v_pk_fma_f32 v[56:57], v[42:43], v[42:43], v[50:51] op_sel_hi:[1,1,0]
	v_mul_f32_e32 v54, v32, v32
	v_mul_f32_e32 v56, v33, v33
	v_mul_f32_e32 v52, v34, v34
	v_mul_f32_e32 v50, v35, v35
	v_pk_add_f32 v[54:55], v[54:55], v[56:57]
	v_pk_add_f32 v[50:51], v[52:53], v[50:51]
	v_add_u32_e32 v48, 0x90, v166
	v_pk_add_f32 v[50:51], v[54:55], v[50:51]
	s_nop 0
	v_add_f32_e32 v49, v50, v51
	ds_bpermute_b32 v50, v158, v49
	s_waitcnt lgkmcnt(0)
	v_add_f32_e32 v49, v49, v50
	ds_bpermute_b32 v50, v159, v49
	s_waitcnt lgkmcnt(0)
	v_add_f32_e32 v49, v49, v50
	v_fmamk_f32 v49, v49, 0x3c800000, v199
	v_cmp_gt_f32_e32 vcc, s19, v49
	v_mul_f32_e32 v50, 0x4f800000, v49
	s_nop 0
	v_cndmask_b32_e32 v49, v49, v50, vcc
	v_sqrt_f32_e32 v50, v49
	s_nop 0
	v_add_u32_e32 v51, -1, v50
	v_fma_f32 v52, -v51, v50, v49
	v_cmp_ge_f32_e64 s[0:1], 0, v52
	v_add_u32_e32 v52, 1, v50
	s_nop 0
	v_cndmask_b32_e64 v51, v50, v51, s[0:1]
	v_fma_f32 v50, -v52, v50, v49
	v_cmp_lt_f32_e64 s[0:1], 0, v50
	s_nop 1
	v_cndmask_b32_e64 v50, v51, v52, s[0:1]
	v_mul_f32_e32 v51, 0x37800000, v50
	v_cndmask_b32_e32 v50, v50, v51, vcc
	v_cmp_class_f32_e32 vcc, v49, v201
	s_nop 1
	v_cndmask_b32_e32 v49, v50, v49, vcc
	v_div_scale_f32 v50, s[0:1], v49, v49, 1.0
	v_rcp_f32_e32 v51, v50
	s_nop 0
	v_fma_f32 v52, -v50, v51, 1.0
	v_fmac_f32_e32 v51, v52, v51
	v_div_scale_f32 v52, vcc, 1.0, v49, 1.0
	v_mul_f32_e32 v53, v52, v51
	v_fma_f32 v54, -v50, v53, v52
	v_fmac_f32_e32 v53, v54, v51
	v_fma_f32 v50, -v50, v53, v52
	v_div_fmas_f32 v50, v50, v51, v53
	v_div_fixup_f32 v66, v50, v49, 1.0
	v_ashrrev_i32_e32 v49, 31, v48
	v_lshl_add_u64 v[50:51], v[144:145], 0, v[48:49]
	v_lshlrev_b64 v[48:49], 5, v[48:49]
	v_lshl_add_u64 v[48:49], v[48:49], 0, s[24:25]
	v_mad_u64_u32 v[64:65], s[0:1], v50, s67, v[146:147]
	v_lshlrev_b64 v[48:49], 2, v[48:49]
	v_mad_i32_i24 v65, v51, s67, v65
	v_lshl_add_u64 v[50:51], s[26:27], 0, v[48:49]
	v_lshl_add_u64 v[48:49], s[42:43], 0, v[48:49]
	v_lshl_add_u64 v[68:69], v[50:51], 0, v[160:161]
	v_lshl_add_u64 v[70:71], v[48:49], 0, v[160:161]
	global_load_dwordx4 v[52:55], v[68:69], off
	global_load_dwordx4 v[48:51], v[70:71], off
	global_load_dwordx4 v[60:63], v160, s[6:7]
	global_load_dwordx4 v[56:59], v160, s[6:7] offset:128
	global_load_dwordx4 v[230:233], v[68:69], off offset:16
	global_load_dwordx4 v[234:237], v[70:71], off offset:16
	global_load_dwordx4 v[238:241], v160, s[6:7] offset:16
	global_load_dwordx4 v[242:245], v160, s[6:7] offset:144
	v_pk_mul_f32 v[40:41], v[40:41], v[66:67] op_sel_hi:[1,0]
	v_pk_mul_f32 v[42:43], v[42:43], v[66:67] op_sel_hi:[1,0]
	v_pk_mul_f32 v[46:47], v[46:47], v[66:67] op_sel_hi:[1,0]
	v_pk_mul_f32 v[44:45], v[44:45], v[66:67] op_sel_hi:[1,0]
	v_pk_mul_f32 v[32:33], v[32:33], v[66:67] op_sel_hi:[1,0]
	v_pk_mul_f32 v[34:35], v[34:35], v[66:67] op_sel_hi:[1,0]
	v_pk_mul_f32 v[38:39], v[38:39], v[66:67] op_sel_hi:[1,0]
	v_pk_mul_f32 v[36:37], v[36:37], v[66:67] op_sel_hi:[1,0]
	s_waitcnt vmcnt(5)
	v_pk_mul_f32 v[44:45], v[60:61], v[44:45]
	s_waitcnt vmcnt(4)
	v_pk_mul_f32 v[42:43], v[58:59], v[42:43]
	v_pk_mul_f32 v[40:41], v[56:57], v[40:41]
	v_pk_mul_f32 v[46:47], v[62:63], v[46:47]
	v_pk_mul_f32 v[56:57], v[48:49], v[40:41]
	v_pk_mul_f32 v[58:59], v[50:51], v[42:43]
	v_pk_mul_f32 v[40:41], v[52:53], v[40:41]
	v_pk_fma_f32 v[58:59], v[54:55], v[46:47], v[58:59] neg_lo:[0,0,1] neg_hi:[0,0,1]
	v_pk_fma_f32 v[56:57], v[52:53], v[44:45], v[56:57] neg_lo:[0,0,1] neg_hi:[0,0,1]
	v_pk_mul_f32 v[42:43], v[54:55], v[42:43]
	v_pk_fma_f32 v[44:45], v[48:49], v[44:45], v[40:41]
	v_pk_fma_f32 v[42:43], v[50:51], v[46:47], v[42:43]
	v_cvt_pk_bf16_f32 v40, v56, v57
	v_cvt_pk_bf16_f32 v41, v58, v59
	v_cvt_pk_bf16_f32 v44, v44, v45
	s_nop 0
	v_cvt_pk_bf16_f32 v45, v42, v43
	s_waitcnt vmcnt(1)
	v_pk_mul_f32 v[36:37], v[36:37], v[238:239]
	s_waitcnt vmcnt(0)
; __device__ __forceinline__ unsigned cvt_pk_bf16(float lo, float hi) { unsigned r; asm volatile("v_cvt_pk_bf16_f32 %0, %1, %2" : "=v"(r) : "v"(lo), "v"(hi)); return r; }
;     __device__ __forceinline__ void operator()(const f32x4 (&acc)[2][2][4][2], const Unit& u, int wr_, int wc_, int fr_, int fq_) const {
;     ...
;                 for (int m = 0; m < 4; ++m) { int rl = ai * HALF + wr * 64 + m * 16 + fr; asm volatile("" : "+v"(rl)); float s = 0.f;
; #pragma unroll
;                     for (int bj = 0; bj < 2; ++bj)
; #pragma unroll
;                         for (int n = 0; n < 2; ++n) { const f32x4 x = acc[ai][bj][m][n]; s += (x[0] * x[0] + x[1] * x[1]) + (x[2] * x[2] + x[3] * x[3]); }
;                     s += __shfl_xor(s, 16); s += __shfl_xor(s, 32);
;                     const float rr = 1.0f / sqrtf(s * (1.0f / 64.0f) + RMS_EPS_F);
;                     const size_t t = (size_t)u.pm * BM + rl;
;                     bf16_t* qrow = Q + ((size_t)(b * 4 + wc) * 8192 + s0 + rl) * 192 + 128;
;                     u32x4 wa, wb;
; #pragma unroll
;                     for (int n = 0; n < 2; ++n) { const int j0 = 8 * fq + 4 * n;
;                         const f32x4 c4 = *(const f32x4*)(cosT + t * 32 + j0), s4 = *(const f32x4*)(sinT + t * 32 + j0);
;                         const f32x4 g1 = *(const f32x4*)(gn_rope + j0), g2 = *(const f32x4*)(gn_rope + 32 + j0);
;                         const f32x4 y1 = acc[ai][0][m][n] * rr * g1, y2 = acc[ai][1][m][n] * rr * g2;
;                         const f32x4 o1 = y1 * c4 - y2 * s4, o2 = y2 * c4 + y1 * s4;
;                         wa[2 * n] = cvt_pk_bf16(o1[0], o1[1]); wa[2 * n + 1] = cvt_pk_bf16(o1[2], o1[3]); wb[2 * n] = cvt_pk_bf16(o2[0], o2[1]); wb[2 * n + 1] = cvt_pk_bf16(o2[2], o2[3]); }
;                     *(u32x4*)(qrow + 8 * fq) = wa; *(u32x4*)(qrow + 32 + 8 * fq) = wb;
;                     asm volatile("" ::: "memory"); }
	v_pk_mul_f32 v[34:35], v[34:35], v[244:245]
	v_pk_mul_f32 v[32:33], v[32:33], v[242:243]
	v_pk_mul_f32 v[38:39], v[38:39], v[240:241]
	v_pk_mul_f32 v[42:43], v[234:235], v[32:33]
	v_pk_mul_f32 v[54:55], v[236:237], v[34:35]
	v_pk_mul_f32 v[34:35], v[232:233], v[34:35]
	v_pk_fma_f32 v[42:43], v[230:231], v[36:37], v[42:43] neg_lo:[0,0,1] neg_hi:[0,0,1]
	v_pk_mul_f32 v[32:33], v[230:231], v[32:33]
	v_pk_fma_f32 v[34:35], v[236:237], v[38:39], v[34:35]
	v_pk_fma_f32 v[54:55], v[232:233], v[38:39], v[54:55] neg_lo:[0,0,1] neg_hi:[0,0,1]
	v_pk_fma_f32 v[32:33], v[234:235], v[36:37], v[32:33]
	v_cvt_pk_bf16_f32 v42, v42, v43
	v_cvt_pk_bf16_f32 v43, v54, v55
	v_pk_mul_f32 v[36:37], v[28:29], v[28:29]
	v_cvt_pk_bf16_f32 v46, v32, v33
	v_cvt_pk_bf16_f32 v47, v34, v35
	v_pk_mul_f32 v[34:35], v[30:31], v[30:31]
	v_lshl_add_u64 v[32:33], v[64:65], 0, v[128:129]
	v_pk_mov_b32 v[38:39], v[36:37], v[34:35] op_sel:[1,0]
	v_mov_b32_e32 v37, v35
	v_pk_add_f32 v[34:35], v[38:39], v[36:37]
	v_pk_mul_f32 v[36:37], v[22:23], v[22:23]
	v_pk_add_f32 v[34:35], v[34:35], v[34:35] op_sel_hi:[0,1]
	v_pk_mul_f32 v[38:39], v[20:21], v[20:21]
	global_store_dwordx4 v[32:33], v[40:43], off offset:256
	global_store_dwordx4 v[32:33], v[44:47], off offset:320
	v_mul_f32_e32 v34, v24, v24
	v_pk_mov_b32 v[40:41], v[38:39], v[36:37] op_sel:[1,0]
	v_mov_b32_e32 v39, v37
	v_pk_add_f32 v[36:37], v[40:41], v[38:39]
	v_pk_fma_f32 v[38:39], v[24:25], v[24:25], v[34:35] op_sel_hi:[1,1,0]
	v_mul_f32_e32 v34, v26, v26
	v_pk_add_f32 v[36:37], v[36:37], v[36:37] op_sel_hi:[0,1]
	v_pk_fma_f32 v[40:41], v[26:27], v[26:27], v[34:35] op_sel_hi:[1,1,0]
	v_mul_f32_e32 v38, v16, v16
	v_mul_f32_e32 v40, v17, v17
	v_mul_f32_e32 v36, v18, v18
	v_mul_f32_e32 v34, v19, v19
	v_pk_add_f32 v[38:39], v[38:39], v[40:41]
	v_pk_add_f32 v[34:35], v[36:37], v[34:35]
	v_add_u32_e32 v32, 0xa0, v166
	v_pk_add_f32 v[34:35], v[38:39], v[34:35]
	s_nop 0
	v_add_f32_e32 v33, v34, v35
	ds_bpermute_b32 v34, v158, v33
	s_waitcnt lgkmcnt(0)
	v_add_f32_e32 v33, v33, v34
	ds_bpermute_b32 v34, v159, v33
	s_waitcnt lgkmcnt(0)
	v_add_f32_e32 v33, v33, v34
	v_fmamk_f32 v33, v33, 0x3c800000, v199
	v_cmp_gt_f32_e32 vcc, s19, v33
	v_mul_f32_e32 v34, 0x4f800000, v33
	s_nop 0
	v_cndmask_b32_e32 v33, v33, v34, vcc
	v_sqrt_f32_e32 v34, v33
	s_nop 0
	v_add_u32_e32 v35, -1, v34
	v_fma_f32 v36, -v35, v34, v33
	v_cmp_ge_f32_e64 s[0:1], 0, v36
	v_add_u32_e32 v36, 1, v34
	s_nop 0
	v_cndmask_b32_e64 v35, v34, v35, s[0:1]
	v_fma_f32 v34, -v36, v34, v33
	v_cmp_lt_f32_e64 s[0:1], 0, v34
	s_nop 1
	v_cndmask_b32_e64 v34, v35, v36, s[0:1]
	v_mul_f32_e32 v35, 0x37800000, v34
	v_cndmask_b32_e32 v34, v34, v35, vcc
	v_cmp_class_f32_e32 vcc, v33, v201
	s_nop 1
	v_cndmask_b32_e32 v33, v34, v33, vcc
	v_div_scale_f32 v34, s[0:1], v33, v33, 1.0
	v_rcp_f32_e32 v35, v34
	s_nop 0
	v_fma_f32 v36, -v34, v35, 1.0
	v_fmac_f32_e32 v35, v36, v35
	v_div_scale_f32 v36, vcc, 1.0, v33, 1.0
	v_mul_f32_e32 v37, v36, v35
	v_fma_f32 v38, -v34, v37, v36
	v_fmac_f32_e32 v37, v38, v35
	v_fma_f32 v34, -v34, v37, v36
	v_div_fmas_f32 v34, v34, v35, v37
	v_div_fixup_f32 v50, v34, v33, 1.0
	v_ashrrev_i32_e32 v33, 31, v32
	v_lshl_add_u64 v[34:35], v[144:145], 0, v[32:33]
	v_lshlrev_b64 v[32:33], 5, v[32:33]
	v_lshl_add_u64 v[32:33], v[32:33], 0, s[24:25]
	v_mad_u64_u32 v[48:49], s[0:1], v34, s67, v[146:147]
	v_lshlrev_b64 v[32:33], 2, v[32:33]
	v_mad_i32_i24 v49, v35, s67, v49
	v_lshl_add_u64 v[34:35], s[26:27], 0, v[32:33]
	v_lshl_add_u64 v[32:33], s[42:43], 0, v[32:33]
	v_lshl_add_u64 v[52:53], v[34:35], 0, v[160:161]
	v_lshl_add_u64 v[54:55], v[32:33], 0, v[160:161]
	global_load_dwordx4 v[36:39], v[52:53], off
	global_load_dwordx4 v[32:35], v[54:55], off
	global_load_dwordx4 v[44:47], v160, s[6:7]
	global_load_dwordx4 v[40:43], v160, s[6:7] offset:128
	global_load_dwordx4 v[230:233], v[52:53], off offset:16
	global_load_dwordx4 v[234:237], v[54:55], off offset:16
	global_load_dwordx4 v[238:241], v160, s[6:7] offset:16
	global_load_dwordx4 v[242:245], v160, s[6:7] offset:144
	v_pk_mul_f32 v[24:25], v[24:25], v[50:51] op_sel_hi:[1,0]
	v_pk_mul_f32 v[26:27], v[26:27], v[50:51] op_sel_hi:[1,0]
	v_pk_mul_f32 v[30:31], v[30:31], v[50:51] op_sel_hi:[1,0]
	v_pk_mul_f32 v[28:29], v[28:29], v[50:51] op_sel_hi:[1,0]
	v_pk_mul_f32 v[16:17], v[16:17], v[50:51] op_sel_hi:[1,0]
	v_pk_mul_f32 v[18:19], v[18:19], v[50:51] op_sel_hi:[1,0]
	v_pk_mul_f32 v[22:23], v[22:23], v[50:51] op_sel_hi:[1,0]
	v_pk_mul_f32 v[20:21], v[20:21], v[50:51] op_sel_hi:[1,0]
	s_waitcnt vmcnt(5)
	v_pk_mul_f32 v[28:29], v[44:45], v[28:29]
	s_waitcnt vmcnt(4)
	v_pk_mul_f32 v[26:27], v[42:43], v[26:27]
	v_pk_mul_f32 v[24:25], v[40:41], v[24:25]
	v_pk_mul_f32 v[30:31], v[46:47], v[30:31]
	v_pk_mul_f32 v[40:41], v[32:33], v[24:25]
	v_pk_mul_f32 v[42:43], v[34:35], v[26:27]
	v_pk_mul_f32 v[24:25], v[36:37], v[24:25]
	v_pk_fma_f32 v[42:43], v[38:39], v[30:31], v[42:43] neg_lo:[0,0,1] neg_hi:[0,0,1]
	v_pk_fma_f32 v[40:41], v[36:37], v[28:29], v[40:41] neg_lo:[0,0,1] neg_hi:[0,0,1]
	v_pk_mul_f32 v[26:27], v[38:39], v[26:27]
	v_pk_fma_f32 v[28:29], v[32:33], v[28:29], v[24:25]
	v_pk_fma_f32 v[26:27], v[34:35], v[30:31], v[26:27]
	v_cvt_pk_bf16_f32 v24, v40, v41
	v_cvt_pk_bf16_f32 v25, v42, v43
	v_cvt_pk_bf16_f32 v28, v28, v29
	s_nop 0
	v_cvt_pk_bf16_f32 v29, v26, v27
	s_waitcnt vmcnt(1)
	v_pk_mul_f32 v[20:21], v[20:21], v[238:239]
	s_waitcnt vmcnt(0)
; __device__ __forceinline__ unsigned cvt_pk_bf16(float lo, float hi) { unsigned r; asm volatile("v_cvt_pk_bf16_f32 %0, %1, %2" : "=v"(r) : "v"(lo), "v"(hi)); return r; }
;     __device__ __forceinline__ void operator()(const f32x4 (&acc)[2][2][4][2], const Unit& u, int wr_, int wc_, int fr_, int fq_) const {
;     ...
;                 for (int m = 0; m < 4; ++m) { int rl = ai * HALF + wr * 64 + m * 16 + fr; asm volatile("" : "+v"(rl)); float s = 0.f;
; #pragma unroll
;                     for (int bj = 0; bj < 2; ++bj)
; #pragma unroll
;                         for (int n = 0; n < 2; ++n) { const f32x4 x = acc[ai][bj][m][n]; s += (x[0] * x[0] + x[1] * x[1]) + (x[2] * x[2] + x[3] * x[3]); }
;                     s += __shfl_xor(s, 16); s += __shfl_xor(s, 32);
;                     const float rr = 1.0f / sqrtf(s * (1.0f / 64.0f) + RMS_EPS_F);
;                     const size_t t = (size_t)u.pm * BM + rl;
;                     bf16_t* qrow = Q + ((size_t)(b * 4 + wc) * 8192 + s0 + rl) * 192 + 128;
;                     u32x4 wa, wb;
; #pragma unroll
;                     for (int n = 0; n < 2; ++n) { const int j0 = 8 * fq + 4 * n;
;                         const f32x4 c4 = *(const f32x4*)(cosT + t * 32 + j0), s4 = *(const f32x4*)(sinT + t * 32 + j0);
;                         const f32x4 g1 = *(const f32x4*)(gn_rope + j0), g2 = *(const f32x4*)(gn_rope + 32 + j0);
;                         const f32x4 y1 = acc[ai][0][m][n] * rr * g1, y2 = acc[ai][1][m][n] * rr * g2;
;                         const f32x4 o1 = y1 * c4 - y2 * s4, o2 = y2 * c4 + y1 * s4;
;                         wa[2 * n] = cvt_pk_bf16(o1[0], o1[1]); wa[2 * n + 1] = cvt_pk_bf16(o1[2], o1[3]); wb[2 * n] = cvt_pk_bf16(o2[0], o2[1]); wb[2 * n + 1] = cvt_pk_bf16(o2[2], o2[3]); }
;                     *(u32x4*)(qrow + 8 * fq) = wa; *(u32x4*)(qrow + 32 + 8 * fq) = wb;
;                     asm volatile("" ::: "memory"); }
	v_pk_mul_f32 v[18:19], v[18:19], v[244:245]
	v_pk_mul_f32 v[16:17], v[16:17], v[242:243]
	v_pk_mul_f32 v[22:23], v[22:23], v[240:241]
	v_pk_mul_f32 v[26:27], v[234:235], v[16:17]
	v_pk_mul_f32 v[38:39], v[236:237], v[18:19]
	v_pk_mul_f32 v[18:19], v[232:233], v[18:19]
	v_pk_fma_f32 v[26:27], v[230:231], v[20:21], v[26:27] neg_lo:[0,0,1] neg_hi:[0,0,1]
	v_pk_mul_f32 v[16:17], v[230:231], v[16:17]
	v_pk_fma_f32 v[18:19], v[236:237], v[22:23], v[18:19]
	v_pk_fma_f32 v[38:39], v[232:233], v[22:23], v[38:39] neg_lo:[0,0,1] neg_hi:[0,0,1]
	v_pk_fma_f32 v[16:17], v[234:235], v[20:21], v[16:17]
	v_cvt_pk_bf16_f32 v26, v26, v27
	v_cvt_pk_bf16_f32 v27, v38, v39
	v_pk_mul_f32 v[20:21], v[12:13], v[12:13]
	v_cvt_pk_bf16_f32 v30, v16, v17
	v_cvt_pk_bf16_f32 v31, v18, v19
	v_pk_mul_f32 v[18:19], v[14:15], v[14:15]
	v_lshl_add_u64 v[16:17], v[48:49], 0, v[128:129]
	v_pk_mov_b32 v[22:23], v[20:21], v[18:19] op_sel:[1,0]
	v_mov_b32_e32 v21, v19
	v_pk_add_f32 v[18:19], v[22:23], v[20:21]
	v_pk_mul_f32 v[20:21], v[6:7], v[6:7]
	v_pk_add_f32 v[18:19], v[18:19], v[18:19] op_sel_hi:[0,1]
	v_pk_mul_f32 v[22:23], v[4:5], v[4:5]
	global_store_dwordx4 v[16:17], v[24:27], off offset:256
	global_store_dwordx4 v[16:17], v[28:31], off offset:320
	v_mul_f32_e32 v18, v8, v8
	v_pk_mov_b32 v[24:25], v[22:23], v[20:21] op_sel:[1,0]
	v_mov_b32_e32 v23, v21
	v_pk_add_f32 v[20:21], v[24:25], v[22:23]
	v_pk_fma_f32 v[22:23], v[8:9], v[8:9], v[18:19] op_sel_hi:[1,1,0]
	v_mul_f32_e32 v18, v10, v10
	v_pk_add_f32 v[20:21], v[20:21], v[20:21] op_sel_hi:[0,1]
	v_pk_fma_f32 v[24:25], v[10:11], v[10:11], v[18:19] op_sel_hi:[1,1,0]
	v_mul_f32_e32 v22, v0, v0
	v_mul_f32_e32 v24, v1, v1
	v_mul_f32_e32 v20, v2, v2
	v_mul_f32_e32 v18, v3, v3
	v_pk_add_f32 v[22:23], v[22:23], v[24:25]
	v_pk_add_f32 v[18:19], v[20:21], v[18:19]
	v_add_u32_e32 v16, 0xb0, v166
	v_pk_add_f32 v[18:19], v[22:23], v[18:19]
	s_nop 0
	v_add_f32_e32 v17, v18, v19
	ds_bpermute_b32 v18, v158, v17
	s_waitcnt lgkmcnt(0)
	v_add_f32_e32 v17, v17, v18
	ds_bpermute_b32 v18, v159, v17
	s_waitcnt lgkmcnt(0)
	v_add_f32_e32 v17, v17, v18
	v_fmamk_f32 v17, v17, 0x3c800000, v199
	v_cmp_gt_f32_e32 vcc, s19, v17
	v_mul_f32_e32 v18, 0x4f800000, v17
	s_nop 0
	v_cndmask_b32_e32 v17, v17, v18, vcc
	v_sqrt_f32_e32 v18, v17
	s_nop 0
	v_add_u32_e32 v19, -1, v18
	v_fma_f32 v20, -v19, v18, v17
	v_cmp_ge_f32_e64 s[0:1], 0, v20
	v_add_u32_e32 v20, 1, v18
	s_nop 0
	v_cndmask_b32_e64 v19, v18, v19, s[0:1]
	v_fma_f32 v18, -v20, v18, v17
	v_cmp_lt_f32_e64 s[0:1], 0, v18
	s_nop 1
	v_cndmask_b32_e64 v18, v19, v20, s[0:1]
	v_mul_f32_e32 v19, 0x37800000, v18
	v_cndmask_b32_e32 v18, v18, v19, vcc
	v_cmp_class_f32_e32 vcc, v17, v201
	s_nop 1
	v_cndmask_b32_e32 v17, v18, v17, vcc
	v_div_scale_f32 v18, s[0:1], v17, v17, 1.0
	v_rcp_f32_e32 v19, v18
	s_nop 0
	v_fma_f32 v20, -v18, v19, 1.0
	v_fmac_f32_e32 v19, v20, v19
	v_div_scale_f32 v20, vcc, 1.0, v17, 1.0
	v_mul_f32_e32 v21, v20, v19
	v_fma_f32 v22, -v18, v21, v20
	v_fmac_f32_e32 v21, v22, v19
	v_fma_f32 v18, -v18, v21, v20
	v_div_fmas_f32 v18, v18, v19, v21
	v_div_fixup_f32 v34, v18, v17, 1.0
	v_ashrrev_i32_e32 v17, 31, v16
	v_lshl_add_u64 v[18:19], v[144:145], 0, v[16:17]
	v_lshlrev_b64 v[16:17], 5, v[16:17]
	v_lshl_add_u64 v[16:17], v[16:17], 0, s[24:25]
	v_mad_u64_u32 v[32:33], s[0:1], v18, s67, v[146:147]
	v_lshlrev_b64 v[16:17], 2, v[16:17]
	v_mad_i32_i24 v33, v19, s67, v33
	v_lshl_add_u64 v[18:19], s[26:27], 0, v[16:17]
	v_lshl_add_u64 v[16:17], s[42:43], 0, v[16:17]
	v_lshl_add_u64 v[36:37], v[18:19], 0, v[160:161]
	v_lshl_add_u64 v[38:39], v[16:17], 0, v[160:161]
	global_load_dwordx4 v[20:23], v[36:37], off
	global_load_dwordx4 v[16:19], v[38:39], off
	global_load_dwordx4 v[28:31], v160, s[6:7]
	global_load_dwordx4 v[24:27], v160, s[6:7] offset:128
	global_load_dwordx4 v[230:233], v[36:37], off offset:16
	global_load_dwordx4 v[234:237], v[38:39], off offset:16
	global_load_dwordx4 v[238:241], v160, s[6:7] offset:16
	global_load_dwordx4 v[242:245], v160, s[6:7] offset:144
	v_pk_mul_f32 v[8:9], v[8:9], v[34:35] op_sel_hi:[1,0]
	v_pk_mul_f32 v[10:11], v[10:11], v[34:35] op_sel_hi:[1,0]
	v_pk_mul_f32 v[14:15], v[14:15], v[34:35] op_sel_hi:[1,0]
	v_pk_mul_f32 v[12:13], v[12:13], v[34:35] op_sel_hi:[1,0]
	v_pk_mul_f32 v[0:1], v[0:1], v[34:35] op_sel_hi:[1,0]
	v_pk_mul_f32 v[4:5], v[4:5], v[34:35] op_sel_hi:[1,0]
	v_pk_mul_f32 v[2:3], v[2:3], v[34:35] op_sel_hi:[1,0]
	v_pk_mul_f32 v[6:7], v[6:7], v[34:35] op_sel_hi:[1,0]
	s_mov_b64 s[0:1], -1
	s_and_b64 vcc, exec, s[2:3]
	s_waitcnt vmcnt(5)
	v_pk_mul_f32 v[12:13], v[28:29], v[12:13]
	s_waitcnt vmcnt(4)
	v_pk_mul_f32 v[10:11], v[26:27], v[10:11]
	v_pk_mul_f32 v[8:9], v[24:25], v[8:9]
	v_pk_mul_f32 v[14:15], v[30:31], v[14:15]
	v_pk_mul_f32 v[24:25], v[16:17], v[8:9]
	v_pk_mul_f32 v[26:27], v[18:19], v[10:11]
	v_pk_mul_f32 v[8:9], v[20:21], v[8:9]
	v_pk_fma_f32 v[26:27], v[22:23], v[14:15], v[26:27] neg_lo:[0,0,1] neg_hi:[0,0,1]
	v_pk_fma_f32 v[24:25], v[20:21], v[12:13], v[24:25] neg_lo:[0,0,1] neg_hi:[0,0,1]
	v_pk_mul_f32 v[10:11], v[22:23], v[10:11]
	v_pk_fma_f32 v[12:13], v[16:17], v[12:13], v[8:9]
	v_pk_fma_f32 v[10:11], v[18:19], v[14:15], v[10:11]
	v_cvt_pk_bf16_f32 v8, v24, v25
	v_cvt_pk_bf16_f32 v9, v26, v27
	v_cvt_pk_bf16_f32 v12, v12, v13
	s_nop 0
	v_cvt_pk_bf16_f32 v13, v10, v11
	s_waitcnt vmcnt(1)
	v_pk_mul_f32 v[4:5], v[4:5], v[238:239]
	s_waitcnt vmcnt(0)
	v_pk_mul_f32 v[0:1], v[0:1], v[242:243]
	v_pk_mul_f32 v[2:3], v[2:3], v[244:245]
	v_pk_mul_f32 v[10:11], v[234:235], v[0:1]
	v_pk_mul_f32 v[0:1], v[230:231], v[0:1]
	v_pk_mul_f32 v[6:7], v[6:7], v[240:241]
	v_pk_mul_f32 v[22:23], v[236:237], v[2:3]
	v_pk_fma_f32 v[10:11], v[230:231], v[4:5], v[10:11] neg_lo:[0,0,1] neg_hi:[0,0,1]
	v_pk_fma_f32 v[0:1], v[234:235], v[4:5], v[0:1]
	v_pk_fma_f32 v[22:23], v[232:233], v[6:7], v[22:23] neg_lo:[0,0,1] neg_hi:[0,0,1]
	v_pk_mul_f32 v[2:3], v[232:233], v[2:3]
	v_cvt_pk_bf16_f32 v10, v10, v11
	v_cvt_pk_bf16_f32 v11, v22, v23
	v_cvt_pk_bf16_f32 v14, v0, v1
	v_lshl_add_u64 v[0:1], v[32:33], 0, v[128:129]
	v_pk_fma_f32 v[2:3], v[236:237], v[6:7], v[2:3]
	s_nop 0
	v_cvt_pk_bf16_f32 v15, v2, v3
	global_store_dwordx4 v[0:1], v[8:11], off offset:256
	global_store_dwordx4 v[0:1], v[12:15], off offset:320
	s_cbranch_vccnz .LBB0_418
	s_andn2_b64 vcc, exec, s[14:15]
	s_cbranch_vccnz .LBB0_417
	s_barrier
	s_branch .LBB0_417
